# MLA loop: QK MFMAs of the odd step read negm from v[66:81] directly; the 8 v_mov_b64 per 2 tiles copy moved out of the loop to the peeled step
# speedup vs baseline: 1.0048x; 1.0048x over previous
.LBB0_553:
	v_add_co_u32_e32 v54, vcc, 0x17f20000, v228
	s_nop 1
	v_addc_co_u32_e32 v55, vcc, 0, v229, vcc
	global_load_dwordx4 v[206:209], v[54:55], off
	v_mfma_f32_32x32x16_bf16 v[82:97], v[50:53], v[150:153], v[66:81]
	v_exp_f32_e32 v50, v114
	v_exp_f32_e32 v51, v115
	v_add_f32_e32 v52, 0, v50
	v_cvt_pk_bf16_f32 v114, v50, v51
	v_exp_f32_e32 v50, v116
	v_add_f32_e32 v52, v51, v52
	v_exp_f32_e32 v51, v117
	v_add_f32_e32 v52, v50, v52
	v_add_f32_e32 v52, v51, v52
	v_cvt_pk_bf16_f32 v115, v50, v51
	v_exp_f32_e32 v116, v118
	v_exp_f32_e32 v117, v119
	v_exp_f32_e32 v118, v120
	v_exp_f32_e32 v119, v121
	v_add_f32_e32 v50, v116, v52
	v_add_f32_e32 v120, v117, v50
	v_mfma_f32_32x32x16_bf16 v[50:65], v[198:201], v[150:153], v[66:81]
	v_cvt_pk_bf16_f32 v116, v116, v117
	v_add_f32_e32 v117, v118, v120
	v_add_f32_e32 v120, v119, v117
	v_cvt_pk_bf16_f32 v117, v118, v119
	v_exp_f32_e32 v118, v122
	v_exp_f32_e32 v119, v123
	v_mfma_f32_32x32x16_bf16 v[82:97], v[202:205], v[146:149], v[82:97]
	v_exp_f32_e32 v121, v125
	v_add_f32_e32 v120, v118, v120
	v_add_f32_e32 v120, v119, v120
	v_cvt_pk_bf16_f32 v118, v118, v119
	v_exp_f32_e32 v119, v124
	s_nop 0
	v_add_f32_e32 v120, v119, v120
	v_add_f32_e32 v120, v121, v120
	v_cvt_pk_bf16_f32 v119, v119, v121
	v_exp_f32_e32 v121, v126
	v_exp_f32_e32 v122, v127
	v_mfma_f32_32x32x16_bf16 v[50:65], v[194:197], v[146:149], v[50:65]
	v_add_f32_e32 v120, v121, v120
	v_add_f32_e32 v123, v122, v120
	v_cvt_pk_bf16_f32 v120, v121, v122
	v_exp_f32_e32 v121, v128
	v_exp_f32_e32 v122, v129
	v_add_f32_e32 v123, v121, v123
	v_add_f32_e32 v123, v122, v123
	v_cvt_pk_bf16_f32 v121, v121, v122
	v_mfma_f32_32x32x16_bf16 v[82:97], v[190:193], v[142:145], v[82:97]
	ds_read_b64_tr_b16 v[190:191], v231 offset:38912
	ds_read_b64_tr_b16 v[192:193], v231 offset:39680
	ds_read_b64_tr_b16 v[126:127], v231 offset:38976
	ds_read_b64_tr_b16 v[128:129], v231 offset:39744
	v_exp_f32_e32 v98, v98
	v_exp_f32_e32 v99, v99
	v_add_f32_e32 v122, v98, v123
	v_add_f32_e32 v123, v99, v122
	v_cvt_pk_bf16_f32 v122, v98, v99
	v_mfma_f32_32x32x16_bf16 v[50:65], v[186:189], v[142:145], v[50:65]
	v_exp_f32_e32 v98, v100
	v_exp_f32_e32 v99, v101
	ds_read_b64_tr_b16 v[186:187], v231 offset:41984
	ds_read_b64_tr_b16 v[188:189], v231 offset:42752
	v_add_f32_e32 v100, v98, v123
	v_add_f32_e32 v100, v99, v100
	v_cvt_pk_bf16_f32 v123, v98, v99
	v_mfma_f32_32x32x16_bf16 v[82:97], v[182:185], v[138:141], v[82:97]
	v_exp_f32_e32 v98, v102
	v_exp_f32_e32 v99, v103
	ds_read_b64_tr_b16 v[182:183], v231 offset:42048
	ds_read_b64_tr_b16 v[184:185], v231 offset:42816
	v_add_f32_e32 v100, v98, v100
	v_add_f32_e32 v100, v99, v100
	v_cvt_pk_bf16_f32 v124, v98, v99
	v_mfma_f32_32x32x16_bf16 v[50:65], v[178:181], v[138:141], v[50:65]
	v_exp_f32_e32 v98, v104
	v_exp_f32_e32 v99, v105
	ds_read_b64_tr_b16 v[210:211], v231 offset:45056
	ds_read_b64_tr_b16 v[212:213], v231 offset:45824
	v_add_f32_e32 v100, v98, v100
	v_add_f32_e32 v100, v99, v100
	v_cvt_pk_bf16_f32 v125, v98, v99
	v_mfma_f32_32x32x16_bf16 v[82:97], v[174:177], v[134:137], v[82:97]
	v_exp_f32_e32 v98, v106
	v_exp_f32_e32 v99, v107
	ds_read_b64_tr_b16 v[214:215], v231 offset:45120
	ds_read_b64_tr_b16 v[216:217], v231 offset:45888
	v_add_f32_e32 v100, v98, v100
	v_add_f32_e32 v100, v99, v100
	v_cvt_pk_bf16_f32 v102, v98, v99
	v_mfma_f32_32x32x16_bf16 v[50:65], v[170:173], v[134:137], v[50:65]
	v_exp_f32_e32 v98, v108
	v_exp_f32_e32 v99, v109
	ds_read_b64_tr_b16 v[106:107], v231 offset:48128
	ds_read_b64_tr_b16 v[108:109], v231 offset:48896
	v_add_f32_e32 v100, v98, v100
	v_add_f32_e32 v100, v99, v100
	v_cvt_pk_bf16_f32 v103, v98, v99
	v_mfma_f32_32x32x16_bf16 v[82:97], v[166:169], v[130:133], v[82:97]
	v_exp_f32_e32 v98, v110
	v_exp_f32_e32 v99, v111
	ds_read_b64_tr_b16 v[244:245], v231 offset:48192
	ds_read_b64_tr_b16 v[246:247], v231 offset:48960
	v_add_f32_e32 v100, v98, v100
	v_add_f32_e32 v100, v99, v100
	v_cvt_pk_bf16_f32 v104, v98, v99
	v_mfma_f32_32x32x16_bf16 v[50:65], v[158:161], v[130:133], v[50:65]
	v_exp_f32_e32 v98, v112
	v_exp_f32_e32 v99, v113
	v_add_f32_e32 v100, v98, v100
	v_add_f32_e32 v110, v99, v100
	v_cvt_pk_bf16_f32 v105, v98, v99
	s_waitcnt lgkmcnt(14)
	v_mfma_f32_32x32x16_bf16 v[18:33], v[190:193], v[114:117], v[18:33]
	ds_read_b128 v[98:101], v233 offset:13312
	ds_read_b128 v[202:205], v233 offset:19968
	v_add_f32_e32 v242, v0, v110
	s_waitcnt lgkmcnt(14)
	v_mfma_f32_32x32x16_bf16 v[2:17], v[126:129], v[114:117], v[2:17]
	ds_read_b128 v[198:201], v233 offset:13344
	ds_read_b128 v[194:197], v233 offset:20000
	s_waitcnt lgkmcnt(14)
	v_mfma_f32_32x32x16_bf16 v[18:33], v[186:189], v[118:121], v[18:33]
	ds_read_b128 v[190:193], v233 offset:13376
	ds_read_b128 v[186:189], v233 offset:20032
	s_waitcnt lgkmcnt(14)
	v_mfma_f32_32x32x16_bf16 v[2:17], v[182:185], v[118:121], v[2:17]
	ds_read_b128 v[182:185], v233 offset:13408
	ds_read_b128 v[178:181], v233 offset:20064
	s_waitcnt lgkmcnt(14)
	v_mfma_f32_32x32x16_bf16 v[18:33], v[210:213], v[122:125], v[18:33]
	ds_read_b128 v[174:177], v233 offset:13440
	ds_read_b128 v[170:173], v233 offset:20096
	s_waitcnt lgkmcnt(14)
	v_mfma_f32_32x32x16_bf16 v[2:17], v[214:217], v[122:125], v[2:17]
	ds_read_b128 v[166:169], v233 offset:13472
	ds_read_b128 v[158:161], v233 offset:20128
	s_waitcnt lgkmcnt(14)
	v_mfma_f32_32x32x16_bf16 v[18:33], v[106:109], v[102:105], v[18:33]
	s_waitcnt lgkmcnt(12)
	v_mfma_f32_32x32x16_bf16 v[2:17], v[244:247], v[102:105], v[2:17]
	v_mov_b32_e32 v0, v110
	s_nop 1
	v_permlane32_swap_b32_e32 v110, v0
	v_max_f32_e32 v0, v0, v0
	v_max_f32_e32 v102, v110, v110
	v_max_f32_e32 v0, v102, v0
	v_cmp_lt_f32_e32 vcc, s74, v0
	s_cbranch_vccz .LBB0_555
	v_frexp_exp_i32_f32_e32 v0, v0
	v_cvt_f32_i32_e32 v0, v0
	v_cndmask_b32_e32 v35, 0, v0, vcc
	v_exp_f32_e64 v0, -v35
	v_add_f32_e32 v235, v235, v35
	v_xor_b32_e32 v34, 0x80000000, v235
	v_sub_f32_e32 v97, v97, v35
	v_pk_mul_f32 v[32:33], v[32:33], v[0:1] op_sel_hi:[1,0]
	v_pk_mul_f32 v[30:31], v[30:31], v[0:1] op_sel_hi:[1,0]
	v_pk_mul_f32 v[28:29], v[28:29], v[0:1] op_sel_hi:[1,0]
	v_pk_mul_f32 v[26:27], v[26:27], v[0:1] op_sel_hi:[1,0]
	v_pk_mul_f32 v[24:25], v[24:25], v[0:1] op_sel_hi:[1,0]
	v_pk_mul_f32 v[22:23], v[22:23], v[0:1] op_sel_hi:[1,0]
	v_pk_mul_f32 v[20:21], v[20:21], v[0:1] op_sel_hi:[1,0]
	v_pk_mul_f32 v[18:19], v[18:19], v[0:1] op_sel_hi:[1,0]
	v_pk_mul_f32 v[16:17], v[16:17], v[0:1] op_sel_hi:[1,0]
	v_pk_mul_f32 v[14:15], v[14:15], v[0:1] op_sel_hi:[1,0]
	v_pk_mul_f32 v[12:13], v[12:13], v[0:1] op_sel_hi:[1,0]
	v_pk_mul_f32 v[10:11], v[10:11], v[0:1] op_sel_hi:[1,0]
	v_pk_mul_f32 v[8:9], v[8:9], v[0:1] op_sel_hi:[1,0]
	v_pk_mul_f32 v[6:7], v[6:7], v[0:1] op_sel_hi:[1,0]
	v_pk_mul_f32 v[4:5], v[4:5], v[0:1] op_sel_hi:[1,0]
	v_pk_mul_f32 v[2:3], v[2:3], v[0:1] op_sel_hi:[1,0]
	v_sub_f32_e32 v96, v96, v35
	v_sub_f32_e32 v95, v95, v35
	v_sub_f32_e32 v94, v94, v35
	v_sub_f32_e32 v93, v93, v35
	v_sub_f32_e32 v92, v92, v35
	v_sub_f32_e32 v91, v91, v35
	v_sub_f32_e32 v90, v90, v35
	v_sub_f32_e32 v89, v89, v35
	v_sub_f32_e32 v88, v88, v35
	v_sub_f32_e32 v87, v87, v35
	v_sub_f32_e32 v86, v86, v35
	v_sub_f32_e32 v85, v85, v35
	v_sub_f32_e32 v84, v84, v35
	v_sub_f32_e32 v83, v83, v35
	v_sub_f32_e32 v82, v82, v35
	v_sub_f32_e32 v65, v65, v35
	v_sub_f32_e32 v64, v64, v35
	v_sub_f32_e32 v63, v63, v35
	v_sub_f32_e32 v62, v62, v35
	v_sub_f32_e32 v61, v61, v35
	v_sub_f32_e32 v60, v60, v35
	v_sub_f32_e32 v59, v59, v35
	v_sub_f32_e32 v58, v58, v35
	v_sub_f32_e32 v57, v57, v35
	v_sub_f32_e32 v56, v56, v35
	v_sub_f32_e32 v55, v55, v35
	v_sub_f32_e32 v54, v54, v35
	v_sub_f32_e32 v53, v53, v35
	v_sub_f32_e32 v52, v52, v35
	v_sub_f32_e32 v51, v51, v35
	v_sub_f32_e32 v50, v50, v35
	v_mul_f32_e32 v242, v242, v0
	v_mov_b32_e32 v35, v34
	v_mov_b32_e32 v36, v34
	v_mov_b32_e32 v37, v34
	v_mov_b32_e32 v38, v34
	v_mov_b32_e32 v39, v34
	v_mov_b32_e32 v40, v34
	v_mov_b32_e32 v41, v34
	v_mov_b32_e32 v42, v34
	v_mov_b32_e32 v43, v34
	v_mov_b32_e32 v44, v34
	v_mov_b32_e32 v45, v34
	v_mov_b32_e32 v46, v34
	v_mov_b32_e32 v47, v34
	v_mov_b32_e32 v48, v34
	v_mov_b32_e32 v49, v34
	v_mov_b32_e32 v66, v34
	v_mov_b32_e32 v67, v34
	v_mov_b32_e32 v68, v34
	v_mov_b32_e32 v69, v34
	v_mov_b32_e32 v70, v34
	v_mov_b32_e32 v71, v34
	v_mov_b32_e32 v72, v34
	v_mov_b32_e32 v73, v34
	v_mov_b32_e32 v74, v34
	v_mov_b32_e32 v75, v34
	v_mov_b32_e32 v76, v34
	v_mov_b32_e32 v77, v34
	v_mov_b32_e32 v78, v34
	v_mov_b32_e32 v79, v34
	v_mov_b32_e32 v80, v34
	v_mov_b32_e32 v81, v34

; template <int MODE>
; __device__ __forceinline__ void attn_unit(LAS unsigned char* lds, const AttnT& T, int b, int q0, int qcol, int kcol, int vcol, int ocol, float sink_l2, const LAS float* btab, const int wv) {
;     ...
;     for (int t = 0; t + 2 < NT; t += 2) { ATT_STEP(pA0, pA1, pB0, pB1, t); ATT_STEP(pB0, pB1, pA0, pA1, t + 1); }
;     ATT_STEP(pA0, pA1, pB0, pB1, NT - 2);
.LBB0_558:
	s_waitcnt vmcnt(1)
	ds_write_b128 v232, v[162:165] offset:13312
	s_and_saveexec_b64 s[24:25], s[4:5]
	s_cbranch_execnz .LBB0_548
	s_branch .LBB0_549
.LBB0_559:
	v_mov_b64_e32 v[34:35], v[66:67]
	v_mov_b64_e32 v[36:37], v[68:69]
	v_mov_b64_e32 v[38:39], v[70:71]
	v_mov_b64_e32 v[40:41], v[72:73]
	v_mov_b64_e32 v[42:43], v[74:75]
	v_mov_b64_e32 v[44:45], v[76:77]
	v_mov_b64_e32 v[46:47], v[78:79]
	v_mov_b64_e32 v[48:49], v[80:81]
	v_add_co_u32_e32 v66, vcc, 0x7f0000, v222
	s_nop 1
	v_addc_co_u32_e32 v67, vcc, 0, v223, vcc
	global_load_dwordx4 v[102:105], v[66:67], off
	v_exp_f32_e32 v0, v82
	v_exp_f32_e32 v82, v83
	v_mfma_f32_32x32x16_bf16 v[66:81], v[98:101], v[150:153], v[34:49]
	v_add_f32_e32 v83, 0, v0
	v_add_f32_e32 v83, v82, v83
	v_cvt_pk_bf16_f32 v82, v0, v82
	v_exp_f32_e32 v0, v84
	v_exp_f32_e32 v84, v85
	v_add_f32_e32 v83, v0, v83
	v_add_f32_e32 v85, v84, v83
	v_cvt_pk_bf16_f32 v83, v0, v84
	v_exp_f32_e32 v0, v86
	v_exp_f32_e32 v84, v87
	v_mfma_f32_32x32x16_bf16 v[34:49], v[202:205], v[150:153], v[34:49]
	v_exp_f32_e32 v86, v89
	v_add_f32_e32 v85, v0, v85
	v_add_f32_e32 v85, v84, v85
	v_cvt_pk_bf16_f32 v84, v0, v84
	v_exp_f32_e32 v0, v88
	s_nop 0
	v_add_f32_e32 v85, v0, v85
	v_add_f32_e32 v87, v86, v85
	v_cvt_pk_bf16_f32 v85, v0, v86
	v_exp_f32_e32 v0, v90
	v_exp_f32_e32 v86, v91
	v_mfma_f32_32x32x16_bf16 v[66:81], v[198:201], v[146:149], v[66:81]
	v_exp_f32_e32 v88, v93
	v_add_f32_e32 v87, v0, v87
	v_add_f32_e32 v87, v86, v87
	v_cvt_pk_bf16_f32 v86, v0, v86
	v_exp_f32_e32 v0, v92
	s_nop 0
	v_add_f32_e32 v87, v0, v87
	v_add_f32_e32 v89, v88, v87
	v_cvt_pk_bf16_f32 v87, v0, v88
	v_exp_f32_e32 v0, v94
	v_exp_f32_e32 v88, v95
	v_mfma_f32_32x32x16_bf16 v[34:49], v[194:197], v[146:149], v[34:49]
	v_exp_f32_e32 v90, v97
	v_add_f32_e32 v89, v0, v89
	v_add_f32_e32 v89, v88, v89
	v_cvt_pk_bf16_f32 v88, v0, v88
	v_exp_f32_e32 v0, v96
	s_nop 0
	v_add_f32_e32 v89, v0, v89
	v_add_f32_e32 v91, v90, v89
	v_cvt_pk_bf16_f32 v89, v0, v90
	v_exp_f32_e32 v0, v50
	v_mfma_f32_32x32x16_bf16 v[66:81], v[190:193], v[142:145], v[66:81]
	v_exp_f32_e32 v50, v51
	v_add_f32_e32 v51, v0, v91
	ds_read_b64_tr_b16 v[94:95], v231 offset:26624
	ds_read_b64_tr_b16 v[96:97], v231 offset:27392
	ds_read_b64_tr_b16 v[90:91], v231 offset:26688
	ds_read_b64_tr_b16 v[92:93], v231 offset:27456
	v_add_f32_e32 v51, v50, v51
	v_cvt_pk_bf16_f32 v50, v0, v50
	v_mfma_f32_32x32x16_bf16 v[34:49], v[186:189], v[142:145], v[34:49]
	v_exp_f32_e32 v0, v52
	ds_read_b64_tr_b16 v[98:99], v231 offset:29696
	ds_read_b64_tr_b16 v[100:101], v231 offset:30464
	v_exp_f32_e32 v52, v53
	v_add_f32_e32 v51, v0, v51
	v_add_f32_e32 v53, v52, v51
	v_cvt_pk_bf16_f32 v51, v0, v52
	v_mfma_f32_32x32x16_bf16 v[66:81], v[182:185], v[138:141], v[66:81]
	v_exp_f32_e32 v0, v54
	ds_read_b64_tr_b16 v[106:107], v231 offset:29760
	ds_read_b64_tr_b16 v[108:109], v231 offset:30528
	v_exp_f32_e32 v52, v55
	v_add_f32_e32 v53, v0, v53
	v_add_f32_e32 v53, v52, v53
	v_cvt_pk_bf16_f32 v52, v0, v52
	v_exp_f32_e32 v0, v56
	v_exp_f32_e32 v54, v57
	v_mfma_f32_32x32x16_bf16 v[34:49], v[178:181], v[138:141], v[34:49]
	v_add_f32_e32 v53, v0, v53
	v_add_f32_e32 v110, v54, v53
	v_cvt_pk_bf16_f32 v53, v0, v54
	ds_read_b64_tr_b16 v[54:55], v231 offset:32768
	ds_read_b64_tr_b16 v[56:57], v231 offset:33536
	v_exp_f32_e32 v0, v58
	v_mfma_f32_32x32x16_bf16 v[66:81], v[174:177], v[134:137], v[66:81]
	v_exp_f32_e32 v58, v59
	v_add_f32_e32 v59, v0, v110
	ds_read_b64_tr_b16 v[110:111], v231 offset:32832
	ds_read_b64_tr_b16 v[112:113], v231 offset:33600
	v_add_f32_e32 v59, v58, v59
	v_cvt_pk_bf16_f32 v58, v0, v58
	v_mfma_f32_32x32x16_bf16 v[34:49], v[170:173], v[134:137], v[34:49]
	v_exp_f32_e32 v0, v60
	ds_read_b64_tr_b16 v[114:115], v231 offset:35840
	ds_read_b64_tr_b16 v[116:117], v231 offset:36608
	v_exp_f32_e32 v60, v61
	v_add_f32_e32 v59, v0, v59
	v_add_f32_e32 v61, v60, v59
	v_cvt_pk_bf16_f32 v59, v0, v60
	v_mfma_f32_32x32x16_bf16 v[66:81], v[166:169], v[130:133], v[66:81]
	v_exp_f32_e32 v0, v62
	ds_read_b64_tr_b16 v[118:119], v231 offset:35904
	ds_read_b64_tr_b16 v[120:121], v231 offset:36672
	v_exp_f32_e32 v60, v63
	v_add_f32_e32 v61, v0, v61
	v_add_f32_e32 v61, v60, v61
	v_cvt_pk_bf16_f32 v60, v0, v60
	v_mfma_f32_32x32x16_bf16 v[34:49], v[158:161], v[130:133], v[34:49]
	v_exp_f32_e32 v0, v64
	v_exp_f32_e32 v62, v65
	v_add_f32_e32 v61, v0, v61
	v_add_f32_e32 v63, v62, v61
	v_cvt_pk_bf16_f32 v61, v0, v62
	s_waitcnt lgkmcnt(14)
	v_mfma_f32_32x32x16_bf16 v[18:33], v[94:97], v[82:85], v[18:33]
	v_add_f32_e32 v0, v242, v63
	s_waitcnt lgkmcnt(12)
	v_mfma_f32_32x32x16_bf16 v[2:17], v[90:93], v[82:85], v[2:17]
	s_waitcnt lgkmcnt(10)
	v_mfma_f32_32x32x16_bf16 v[18:33], v[98:101], v[86:89], v[18:33]
	s_waitcnt lgkmcnt(8)
	v_mfma_f32_32x32x16_bf16 v[2:17], v[106:109], v[86:89], v[2:17]
	s_waitcnt lgkmcnt(6)
	v_mfma_f32_32x32x16_bf16 v[18:33], v[54:57], v[50:53], v[18:33]
	s_waitcnt lgkmcnt(4)
	v_mfma_f32_32x32x16_bf16 v[2:17], v[110:113], v[50:53], v[2:17]
	s_waitcnt lgkmcnt(2)
	v_mfma_f32_32x32x16_bf16 v[18:33], v[114:117], v[58:61], v[18:33]
	s_waitcnt lgkmcnt(0)
	v_mfma_f32_32x32x16_bf16 v[2:17], v[118:121], v[58:61], v[2:17]
	v_mov_b32_e32 v50, v63
	s_nop 1
	v_permlane32_swap_b32_e32 v63, v50
	v_max_f32_e32 v50, v50, v50
	v_max_f32_e32 v51, v63, v63
	v_max_f32_e32 v50, v51, v50
	v_cmp_lt_f32_e32 vcc, s74, v50
	s_cbranch_vccz .LBB0_524
	v_frexp_exp_i32_f32_e32 v50, v50
	v_cvt_f32_i32_e32 v50, v50
	v_cndmask_b32_e32 v51, 0, v50, vcc
	v_exp_f32_e64 v50, -v51
	v_sub_f32_e32 v81, v81, v51
	v_sub_f32_e32 v80, v80, v51
	v_sub_f32_e32 v79, v79, v51
	v_pk_mul_f32 v[32:33], v[32:33], v[50:51] op_sel_hi:[1,0]
	v_pk_mul_f32 v[30:31], v[30:31], v[50:51] op_sel_hi:[1,0]
	v_pk_mul_f32 v[28:29], v[28:29], v[50:51] op_sel_hi:[1,0]
	v_pk_mul_f32 v[26:27], v[26:27], v[50:51] op_sel_hi:[1,0]
	v_pk_mul_f32 v[24:25], v[24:25], v[50:51] op_sel_hi:[1,0]
	v_pk_mul_f32 v[22:23], v[22:23], v[50:51] op_sel_hi:[1,0]
	v_pk_mul_f32 v[20:21], v[20:21], v[50:51] op_sel_hi:[1,0]
	v_pk_mul_f32 v[18:19], v[18:19], v[50:51] op_sel_hi:[1,0]
	v_pk_mul_f32 v[16:17], v[16:17], v[50:51] op_sel_hi:[1,0]
	v_pk_mul_f32 v[14:15], v[14:15], v[50:51] op_sel_hi:[1,0]
	v_pk_mul_f32 v[12:13], v[12:13], v[50:51] op_sel_hi:[1,0]
	v_pk_mul_f32 v[10:11], v[10:11], v[50:51] op_sel_hi:[1,0]
	v_pk_mul_f32 v[8:9], v[8:9], v[50:51] op_sel_hi:[1,0]
	v_pk_mul_f32 v[6:7], v[6:7], v[50:51] op_sel_hi:[1,0]
	v_pk_mul_f32 v[4:5], v[4:5], v[50:51] op_sel_hi:[1,0]
	v_pk_mul_f32 v[2:3], v[2:3], v[50:51] op_sel_hi:[1,0]
	v_sub_f32_e32 v78, v78, v51
	v_sub_f32_e32 v77, v77, v51
	v_sub_f32_e32 v76, v76, v51
	v_sub_f32_e32 v75, v75, v51
	v_sub_f32_e32 v74, v74, v51
	v_sub_f32_e32 v73, v73, v51
	v_sub_f32_e32 v72, v72, v51
	v_sub_f32_e32 v71, v71, v51
	v_sub_f32_e32 v70, v70, v51
	v_sub_f32_e32 v69, v69, v51
	v_sub_f32_e32 v68, v68, v51
	v_sub_f32_e32 v67, v67, v51
	v_sub_f32_e32 v66, v66, v51
	v_sub_f32_e32 v49, v49, v51
	v_sub_f32_e32 v48, v48, v51
	v_sub_f32_e32 v47, v47, v51
	v_sub_f32_e32 v46, v46, v51
	v_sub_f32_e32 v45, v45, v51
	v_sub_f32_e32 v44, v44, v51
	v_sub_f32_e32 v43, v43, v51
	v_sub_f32_e32 v42, v42, v51
	v_sub_f32_e32 v41, v41, v51
	v_sub_f32_e32 v40, v40, v51
	v_sub_f32_e32 v39, v39, v51
	v_sub_f32_e32 v38, v38, v51
	v_sub_f32_e32 v37, v37, v51
	v_sub_f32_e32 v36, v36, v51
	v_sub_f32_e32 v35, v35, v51
	v_sub_f32_e32 v34, v34, v51
	v_mul_f32_e32 v0, v0, v50
	s_branch .LBB0_524
